# k22: scan loader wave issues the next chunk's LDS-DMA at the top of its step (before its state-chain work) instead of after it
# baseline (speedup 1.0000x reference)
.LBB0_817:
	s_add_i32 s38, s33, -4
	s_cmpk_gt_u32 s38, 0x1fb
	s_cbranch_scc1 .Lscan_dma_skip
	s_mul_i32 s4, s33, 0xcccd
	s_lshr_b32 s4, s4, 18
	s_mul_i32 s4, s4, 5
	s_sub_i32 s4, s33, s4
	s_and_b32 s4, s4, 0xffff
	s_cmp_lg_u32 0, -1
	s_mulk_i32 s4, 0x2900
	s_cselect_b32 s5, 0, 0
	v_lshl_add_u64 v[0:1], v[72:73], 0, s[12:13]
	s_add_i32 s4, s5, s4
	v_lshl_add_u64 v[2:3], v[0:1], 0, s[14:15]
	s_add_i32 s36, s4, 0x19c00
	s_mov_b32 m0, s36
	s_nop 0
	global_load_lds_dwordx4 v[2:3], off
	v_lshl_add_u64 v[2:3], v[0:1], 0, s[16:17]
	s_add_i32 s4, s36, 0x400
	s_mov_b32 m0, s4
	s_nop 0
	global_load_lds_dwordx4 v[2:3], off
	v_lshl_add_u64 v[2:3], v[74:75], 0, s[12:13]
	v_lshl_add_u64 v[4:5], v[2:3], 0, s[18:19]
	s_add_i32 s4, s36, 0x800
	s_mov_b32 m0, s4
	s_nop 0
	global_load_lds_dwordx4 v[4:5], off
	v_lshl_add_u64 v[4:5], v[2:3], 0, s[20:21]
	s_add_i32 s4, s36, 0xc00
	s_mov_b32 m0, s4
	s_nop 0
	global_load_lds_dwordx4 v[4:5], off
	v_lshl_add_u64 v[4:5], v[2:3], 0, s[22:23]
	s_add_i32 s4, s36, 0x1000
	s_mov_b32 m0, s4
	s_nop 0
	global_load_lds_dwordx4 v[4:5], off
	v_lshl_add_u64 v[2:3], v[2:3], 0, s[24:25]
	s_add_i32 s4, s36, 0x1400
	s_mov_b32 m0, s4
	s_nop 0
	global_load_lds_dwordx4 v[2:3], off
	v_lshl_add_u64 v[2:3], v[0:1], 0, s[26:27]
	s_add_i32 s4, s36, 0x1800
	s_mov_b32 m0, s4
	s_nop 0
	global_load_lds_dwordx4 v[2:3], off
	v_lshl_add_u64 v[0:1], v[0:1], 0, s[28:29]
	s_add_i32 s4, s36, 0x1c00
	s_mov_b32 m0, s4
	s_nop 0
	global_load_lds_dwordx4 v[0:1], off
	s_and_saveexec_b64 s[4:5], s[6:7]
	s_cbranch_execz .Lscan_dma_mid
	s_add_i32 s37, s36, 0x2000
	s_mov_b32 m0, s37
	s_nop 0
	global_load_lds_dwordx4 v[70:71], off
	v_lshl_add_u64 v[0:1], v[70:71], 0, s[30:31]
	s_add_i32 s37, s36, 0x2200
	s_mov_b32 m0, s37
	s_nop 0
	global_load_lds_dwordx4 v[0:1], off
.Lscan_dma_mid:
	s_or_b64 exec, exec, s[4:5]
	s_and_saveexec_b64 s[4:5], s[8:9]
	s_cbranch_execz .Lscan_dma_done
	v_lshl_add_u64 v[0:1], v[68:69], 0, s[0:1]
	v_lshl_add_u64 v[0:1], v[0:1], 0, s[10:11]
	s_addk_i32 s36, 0x2800
	s_mov_b32 m0, s36
	s_nop 0
	global_load_lds_dwordx4 v[0:1], off
.Lscan_dma_done:
	s_or_b64 exec, exec, s[4:5]
.Lscan_dma_skip:
	s_cmpk_lt_i32 s38, 0x203
	s_cbranch_scc1 .LBB0_819
	s_cmpk_lg_i32 s38, 0x203
	s_cselect_b64 s[4:5], -1, 0
	s_cbranch_execz .LBB0_820
	s_branch .LBB0_821
